# GLA-C prefix fold software-pipelined: next superchunk loads in flight during the current fold (two register sets), workspace-pointer scalar loads hoisted out of the loop
# baseline (speedup 1.0000x reference)
.LBB0_448:
	s_or_b64 exec, exec, s[8:9]
	s_and_b64 s[8:9], s[44:45], exec
	v_readlane_b32 s8, v252, 43
	s_cselect_b32 s8, s67, s8
	s_cmp_gt_i32 s8, 0
	v_readlane_b32 s78, v252, 35
	s_cselect_b64 s[76:77], -1, 0
	v_readlane_b32 s79, v252, 36
	s_and_b64 s[76:77], s[78:79], s[76:77]
	v_mov_b32_e32 v22, 0
	s_andn2_b64 vcc, exec, s[76:77]
	v_mov_b32_e32 v23, 0
	v_mov_b32_e32 v24, 0
	v_mov_b32_e32 v25, 0
	v_mov_b32_e32 v26, 0
	v_mov_b32_e32 v27, 0
	v_mov_b32_e32 v28, 0
	v_mov_b32_e32 v29, 0
	v_mov_b32_e32 v30, 0
	v_mov_b32_e32 v31, 0
	v_mov_b32_e32 v32, 0
	v_mov_b32_e32 v33, 0
	v_mov_b32_e32 v38, 0
	v_mov_b32_e32 v39, 0
	v_mov_b32_e32 v40, 0
	v_mov_b32_e32 v41, 0
	s_waitcnt lgkmcnt(0)
	s_barrier
	s_cbranch_vccnz .LBB0_452
	s_or_b32 s9, s10, s61
	s_mov_b32 s10, 27
	s_ashr_i32 s11, s10, 31
	s_lshl_b64 s[10:11], s[10:11], 3
	s_add_u32 s10, s0, s10
	s_addc_u32 s11, s1, s11
	s_load_dwordx2 s[10:11], s[10:11], 0x0
	s_mul_i32 s76, s9, 17
	s_ashr_i32 s77, s76, 31
	s_lshl_b64 s[78:79], s[76:77], 15
	v_lshlrev_b32_e32 v2, 2, v106
	s_waitcnt lgkmcnt(0)
	s_add_u32 s9, s10, s78
	s_addc_u32 s11, s11, s79
	s_add_u32 s10, s9, s94
	s_mov_b32 s78, 27
	s_addc_u32 s11, s11, s95
	s_ashr_i32 s79, s78, 31
	s_lshl_b64 s[78:79], s[78:79], 3
	s_add_u32 s78, s0, s78
	s_addc_u32 s79, s1, s79
	s_load_dwordx2 s[78:79], s[78:79], 0x0
	s_lshl_b64 s[80:81], s[76:77], 8
	s_mov_b32 s55, 0x2400000
	s_waitcnt lgkmcnt(0)
	s_add_u32 s9, s78, s80
	s_addc_u32 s15, s79, s81
	s_add_u32 s78, s9, 0x3500000
	s_addc_u32 s79, s15, 0
	s_cmp_lt_u32 s8, 2
	v_lshlrev_b32_e32 v0, 2, v104
	v_lshlrev_b32_e32 v3, 2, v122
	v_lshl_add_u64 v[10:11], s[10:11], 0, v[0:1]
	v_lshl_add_u64 v[12:13], v[10:11], 0, s[86:87]
	v_add_co_u32_e32 v10, vcc, s55, v10
	s_nop 1
	v_addc_co_u32_e32 v11, vcc, 0, v11, vcc
	global_load_dword v42, v2, s[78:79]
	global_load_dword v44, v2, s[78:79] offset:64
	global_load_dword v46, v2, s[78:79] offset:128
	global_load_dword v48, v3, s[78:79]
	global_load_dword v50, v[10:11], off
	global_load_dword v51, v[12:13], off offset:256
	global_load_dword v52, v[12:13], off offset:512
	global_load_dword v53, v[12:13], off offset:768
	global_load_dword v54, v[12:13], off offset:1024
	global_load_dword v55, v[12:13], off offset:1280
	global_load_dword v56, v[12:13], off offset:1536
	global_load_dword v57, v[12:13], off offset:1792
	global_load_dword v58, v[12:13], off offset:2048
	global_load_dword v59, v[12:13], off offset:2304
	global_load_dword v60, v[12:13], off offset:2560
	global_load_dword v61, v[12:13], off offset:2816
	global_load_dword v62, v[12:13], off offset:3072
	global_load_dword v63, v[12:13], off offset:3328
	global_load_dword v64, v[12:13], off offset:3584
	global_load_dword v65, v[12:13], off offset:3840
	s_waitcnt vmcnt(0)
	v_mul_f32_e32 v8, 0, v42
	v_pk_add_f32 v[22:23], v[8:9], v[50:51] op_sel_hi:[0,1]
	v_pk_add_f32 v[24:25], v[8:9], v[52:53] op_sel_hi:[0,1]
	v_mul_f32_e32 v8, 0, v44
	v_pk_add_f32 v[26:27], v[8:9], v[54:55] op_sel_hi:[0,1]
	v_pk_add_f32 v[28:29], v[8:9], v[56:57] op_sel_hi:[0,1]
	v_mul_f32_e32 v8, 0, v46
	v_pk_add_f32 v[30:31], v[8:9], v[58:59] op_sel_hi:[0,1]
	v_pk_add_f32 v[32:33], v[8:9], v[60:61] op_sel_hi:[0,1]
	v_mul_f32_e32 v8, 0, v48
	v_pk_add_f32 v[38:39], v[8:9], v[62:63] op_sel_hi:[0,1]
	v_pk_add_f32 v[40:41], v[8:9], v[64:65] op_sel_hi:[0,1]
	s_cbranch_scc1 .LBB0_452
	s_mov_b32 s9, 1
	s_mov_b32 s10, 16
	s_load_dwordx2 s[98:99], s[0:1], 0xd8
	s_waitcnt lgkmcnt(0)
	s_and_b64 s[78:79], s[44:45], exec
	s_cselect_b32 s11, s9, s10
	s_add_i32 s80, s11, s76
	s_ashr_i32 s81, s80, 31
	s_lshl_b64 s[82:83], s[80:81], 15
	s_add_u32 s11, s98, s82
	s_addc_u32 s15, s99, s83
	s_add_u32 s78, s11, s94
	s_addc_u32 s79, s15, s95
	s_lshl_b64 s[80:81], s[80:81], 8
	v_lshl_add_u64 v[10:11], s[78:79], 0, v[0:1]
	v_lshl_add_u64 v[12:13], v[10:11], 0, s[86:87]
	v_add_co_u32_e32 v10, vcc, s55, v10
	s_add_u32 s11, s98, s80
	s_addc_u32 s15, s99, s81
	s_add_u32 s80, s11, 0x3500000
	s_addc_u32 s81, s15, 0
	v_addc_co_u32_e32 v11, vcc, 0, v11, vcc
	global_load_dword v42, v2, s[80:81]
	global_load_dword v44, v2, s[80:81] offset:64
	global_load_dword v46, v2, s[80:81] offset:128
	global_load_dword v48, v3, s[80:81]
	global_load_dword v50, v[10:11], off
	global_load_dword v51, v[12:13], off offset:256
	global_load_dword v52, v[12:13], off offset:512
	global_load_dword v53, v[12:13], off offset:768
	global_load_dword v54, v[12:13], off offset:1024
	global_load_dword v55, v[12:13], off offset:1280
	global_load_dword v56, v[12:13], off offset:1536
	global_load_dword v57, v[12:13], off offset:1792
	global_load_dword v58, v[12:13], off offset:2048
	global_load_dword v59, v[12:13], off offset:2304
	global_load_dword v60, v[12:13], off offset:2560
	global_load_dword v61, v[12:13], off offset:2816
	global_load_dword v62, v[12:13], off offset:3072
	global_load_dword v63, v[12:13], off offset:3328
	global_load_dword v64, v[12:13], off offset:3584
	global_load_dword v65, v[12:13], off offset:3840
.Lfold_loop:
	s_add_i32 s9, s9, 1
	s_add_i32 s10, s10, -1
	s_cmp_eq_u32 s8, s9
	s_cbranch_scc1 .Lfold_last_a
	s_and_b64 s[78:79], s[44:45], exec
	s_cselect_b32 s11, s9, s10
	s_add_i32 s80, s11, s76
	s_ashr_i32 s81, s80, 31
	s_lshl_b64 s[82:83], s[80:81], 15
	s_add_u32 s11, s98, s82
	s_addc_u32 s15, s99, s83
	s_add_u32 s78, s11, s94
	s_addc_u32 s79, s15, s95
	s_lshl_b64 s[80:81], s[80:81], 8
	v_lshl_add_u64 v[10:11], s[78:79], 0, v[0:1]
	v_lshl_add_u64 v[12:13], v[10:11], 0, s[86:87]
	v_add_co_u32_e32 v10, vcc, s55, v10
	s_add_u32 s11, s98, s80
	s_addc_u32 s15, s99, s81
	s_add_u32 s80, s11, 0x3500000
	s_addc_u32 s81, s15, 0
	v_addc_co_u32_e32 v11, vcc, 0, v11, vcc
	global_load_dword v154, v2, s[80:81]
	global_load_dword v156, v2, s[80:81] offset:64
	global_load_dword v158, v2, s[80:81] offset:128
	global_load_dword v160, v3, s[80:81]
	global_load_dword v162, v[10:11], off
	global_load_dword v163, v[12:13], off offset:256
	global_load_dword v164, v[12:13], off offset:512
	global_load_dword v165, v[12:13], off offset:768
	global_load_dword v166, v[12:13], off offset:1024
	global_load_dword v167, v[12:13], off offset:1280
	global_load_dword v168, v[12:13], off offset:1536
	global_load_dword v169, v[12:13], off offset:1792
	global_load_dword v170, v[12:13], off offset:2048
	global_load_dword v171, v[12:13], off offset:2304
	global_load_dword v172, v[12:13], off offset:2560
	global_load_dword v173, v[12:13], off offset:2816
	global_load_dword v174, v[12:13], off offset:3072
	global_load_dword v175, v[12:13], off offset:3328
	global_load_dword v176, v[12:13], off offset:3584
	global_load_dword v177, v[12:13], off offset:3840
	s_waitcnt vmcnt(20)
	v_pk_fma_f32 v[22:23], v[22:23], v[42:43], v[50:51] op_sel_hi:[1,0,1]
	v_pk_fma_f32 v[24:25], v[24:25], v[42:43], v[52:53] op_sel_hi:[1,0,1]
	v_pk_fma_f32 v[26:27], v[26:27], v[44:45], v[54:55] op_sel_hi:[1,0,1]
	v_pk_fma_f32 v[28:29], v[28:29], v[44:45], v[56:57] op_sel_hi:[1,0,1]
	v_pk_fma_f32 v[30:31], v[30:31], v[46:47], v[58:59] op_sel_hi:[1,0,1]
	v_pk_fma_f32 v[32:33], v[32:33], v[46:47], v[60:61] op_sel_hi:[1,0,1]
	v_pk_fma_f32 v[38:39], v[38:39], v[48:49], v[62:63] op_sel_hi:[1,0,1]
	v_pk_fma_f32 v[40:41], v[40:41], v[48:49], v[64:65] op_sel_hi:[1,0,1]
	s_add_i32 s9, s9, 1
	s_add_i32 s10, s10, -1
	s_cmp_eq_u32 s8, s9
	s_cbranch_scc1 .Lfold_last_b
	s_and_b64 s[78:79], s[44:45], exec
	s_cselect_b32 s11, s9, s10
	s_add_i32 s80, s11, s76
	s_ashr_i32 s81, s80, 31
	s_lshl_b64 s[82:83], s[80:81], 15
	s_add_u32 s11, s98, s82
	s_addc_u32 s15, s99, s83
	s_add_u32 s78, s11, s94
	s_addc_u32 s79, s15, s95
	s_lshl_b64 s[80:81], s[80:81], 8
	v_lshl_add_u64 v[10:11], s[78:79], 0, v[0:1]
	v_lshl_add_u64 v[12:13], v[10:11], 0, s[86:87]
	v_add_co_u32_e32 v10, vcc, s55, v10
	s_add_u32 s11, s98, s80
	s_addc_u32 s15, s99, s81
	s_add_u32 s80, s11, 0x3500000
	s_addc_u32 s81, s15, 0
	v_addc_co_u32_e32 v11, vcc, 0, v11, vcc
	global_load_dword v42, v2, s[80:81]
	global_load_dword v44, v2, s[80:81] offset:64
	global_load_dword v46, v2, s[80:81] offset:128
	global_load_dword v48, v3, s[80:81]
	global_load_dword v50, v[10:11], off
	global_load_dword v51, v[12:13], off offset:256
	global_load_dword v52, v[12:13], off offset:512
	global_load_dword v53, v[12:13], off offset:768
	global_load_dword v54, v[12:13], off offset:1024
	global_load_dword v55, v[12:13], off offset:1280
	global_load_dword v56, v[12:13], off offset:1536
	global_load_dword v57, v[12:13], off offset:1792
	global_load_dword v58, v[12:13], off offset:2048
	global_load_dword v59, v[12:13], off offset:2304
	global_load_dword v60, v[12:13], off offset:2560
	global_load_dword v61, v[12:13], off offset:2816
	global_load_dword v62, v[12:13], off offset:3072
	global_load_dword v63, v[12:13], off offset:3328
	global_load_dword v64, v[12:13], off offset:3584
	global_load_dword v65, v[12:13], off offset:3840
	s_waitcnt vmcnt(20)
	v_pk_fma_f32 v[22:23], v[22:23], v[154:155], v[162:163] op_sel_hi:[1,0,1]
	v_pk_fma_f32 v[24:25], v[24:25], v[154:155], v[164:165] op_sel_hi:[1,0,1]
	v_pk_fma_f32 v[26:27], v[26:27], v[156:157], v[166:167] op_sel_hi:[1,0,1]
	v_pk_fma_f32 v[28:29], v[28:29], v[156:157], v[168:169] op_sel_hi:[1,0,1]
	v_pk_fma_f32 v[30:31], v[30:31], v[158:159], v[170:171] op_sel_hi:[1,0,1]
	v_pk_fma_f32 v[32:33], v[32:33], v[158:159], v[172:173] op_sel_hi:[1,0,1]
	v_pk_fma_f32 v[38:39], v[38:39], v[160:161], v[174:175] op_sel_hi:[1,0,1]
	v_pk_fma_f32 v[40:41], v[40:41], v[160:161], v[176:177] op_sel_hi:[1,0,1]
	s_branch .Lfold_loop
.Lfold_last_a:
	s_waitcnt vmcnt(0)
	v_pk_fma_f32 v[22:23], v[22:23], v[42:43], v[50:51] op_sel_hi:[1,0,1]
	v_pk_fma_f32 v[24:25], v[24:25], v[42:43], v[52:53] op_sel_hi:[1,0,1]
	v_pk_fma_f32 v[26:27], v[26:27], v[44:45], v[54:55] op_sel_hi:[1,0,1]
	v_pk_fma_f32 v[28:29], v[28:29], v[44:45], v[56:57] op_sel_hi:[1,0,1]
	v_pk_fma_f32 v[30:31], v[30:31], v[46:47], v[58:59] op_sel_hi:[1,0,1]
	v_pk_fma_f32 v[32:33], v[32:33], v[46:47], v[60:61] op_sel_hi:[1,0,1]
	v_pk_fma_f32 v[38:39], v[38:39], v[48:49], v[62:63] op_sel_hi:[1,0,1]
	v_pk_fma_f32 v[40:41], v[40:41], v[48:49], v[64:65] op_sel_hi:[1,0,1]
	s_branch .LBB0_452
.Lfold_last_b:
	s_waitcnt vmcnt(0)
	v_pk_fma_f32 v[22:23], v[22:23], v[154:155], v[162:163] op_sel_hi:[1,0,1]
	v_pk_fma_f32 v[24:25], v[24:25], v[154:155], v[164:165] op_sel_hi:[1,0,1]
	v_pk_fma_f32 v[26:27], v[26:27], v[156:157], v[166:167] op_sel_hi:[1,0,1]
	v_pk_fma_f32 v[28:29], v[28:29], v[156:157], v[168:169] op_sel_hi:[1,0,1]
	v_pk_fma_f32 v[30:31], v[30:31], v[158:159], v[170:171] op_sel_hi:[1,0,1]
	v_pk_fma_f32 v[32:33], v[32:33], v[158:159], v[172:173] op_sel_hi:[1,0,1]
	v_pk_fma_f32 v[38:39], v[38:39], v[160:161], v[174:175] op_sel_hi:[1,0,1]
	v_pk_fma_f32 v[40:41], v[40:41], v[160:161], v[176:177] op_sel_hi:[1,0,1]
